# phase 7 scan (chunks 4..7): the sixteen LDS operand loads of the 8-MFMA accP chain issued together, counted lgkmcnt waits
# speedup vs baseline: 1.0013x; 1.0013x over previous
.LBB0_900:
	s_or_b64 exec, exec, s[42:43]
	s_waitcnt lgkmcnt(0)
	s_barrier
	ds_read_b128 v[66:69], v188 offset:8704
	ds_read_b128 v[70:73], v165
	ds_read_b128 v[126:129], v165 offset:32
	ds_read_b128 v[166:169], v188 offset:8736
	ds_read_b128 v[196:199], v188 offset:8768
	ds_read_b128 v[200:203], v165 offset:64
	ds_read_b128 v[204:207], v188 offset:8800
	ds_read_b128 v[208:211], v165 offset:96
	ds_read_b128 v[212:215], v188 offset:8832
	ds_read_b128 v[216:219], v165 offset:128
	ds_read_b128 v[220:223], v188 offset:8864
	ds_read_b128 v[224:227], v165 offset:160
	ds_read_b128 v[228:231], v188 offset:8896
	ds_read_b128 v[232:235], v165 offset:192
	ds_read_b128 v[236:239], v188 offset:8928
	ds_read_b128 v[178:181], v165 offset:224
	s_waitcnt lgkmcnt(14)
	v_mfma_f32_32x32x16_bf16 v[66:81], v[66:69], v[70:73], 0
	v_cvt_pk_bf16_f32 v50, v50, v51
	v_cvt_pk_bf16_f32 v51, v52, v53
	v_cvt_pk_bf16_f32 v52, v54, v55
	v_cvt_pk_bf16_f32 v53, v56, v57
	v_cvt_pk_bf16_f32 v54, v58, v59
	v_cvt_pk_bf16_f32 v55, v60, v61
	v_cvt_pk_bf16_f32 v56, v62, v63
	s_waitcnt lgkmcnt(12)
	v_mfma_f32_32x32x16_bf16 v[66:81], v[166:169], v[126:129], v[66:81]
	v_cvt_pk_bf16_f32 v57, v64, v65
	v_cvt_pk_bf16_f32 v2, v2, v3
	v_cvt_pk_bf16_f32 v3, v4, v5
	v_cvt_pk_bf16_f32 v4, v6, v7
	v_cvt_pk_bf16_f32 v5, v8, v9
	v_cvt_pk_bf16_f32 v6, v10, v11
	s_waitcnt lgkmcnt(10)
	v_mfma_f32_32x32x16_bf16 v[66:81], v[196:199], v[200:203], v[66:81]
	v_cvt_pk_bf16_f32 v7, v12, v13
	v_cvt_pk_bf16_f32 v8, v14, v15
	v_cvt_pk_bf16_f32 v9, v16, v17
	s_waitcnt lgkmcnt(8)
	v_mfma_f32_32x32x16_bf16 v[66:81], v[204:207], v[208:211], v[66:81]
	s_waitcnt lgkmcnt(6)
	v_mfma_f32_32x32x16_bf16 v[66:81], v[212:215], v[216:219], v[66:81]
	s_waitcnt lgkmcnt(4)
	v_mfma_f32_32x32x16_bf16 v[66:81], v[220:223], v[224:227], v[66:81]
	s_waitcnt lgkmcnt(2)
	v_mfma_f32_32x32x16_bf16 v[66:81], v[228:231], v[232:235], v[66:81]
	ds_read2_b64 v[170:173], v195 offset0:128 offset1:130
	ds_read2_b64 v[174:177], v195 offset0:132 offset1:134
	s_waitcnt lgkmcnt(2)
	v_mfma_f32_32x32x16_bf16 v[66:81], v[236:239], v[178:181], v[66:81]
	s_nop 11
	v_cndmask_b32_e64 v82, v66, 0, s[8:9]
	v_cndmask_b32_e64 v95, 0, v67, s[10:11]
	v_cndmask_b32_e64 v67, v68, 0, s[12:13]
	v_cndmask_b32_e64 v68, v69, 0, s[14:15]
	v_cndmask_b32_e64 v69, v70, 0, s[16:17]
	v_cndmask_b32_e64 v70, v71, 0, s[18:19]
	v_cndmask_b32_e64 v71, v72, 0, s[20:21]
	v_cndmask_b32_e64 v72, v73, 0, s[22:23]
	v_cndmask_b32_e64 v66, v82, v66, s[10:11]
	v_cvt_pk_bf16_f32 v67, v67, v68
	v_cvt_pk_bf16_f32 v68, v69, v70
	v_cvt_pk_bf16_f32 v69, v71, v72
	v_cvt_pk_bf16_f32 v66, v66, v95
	v_cndmask_b32_e64 v73, v74, 0, s[24:25]
	v_cndmask_b32_e64 v74, v75, 0, s[26:27]
	v_cndmask_b32_e64 v127, v76, 0, s[28:29]
	v_cndmask_b32_e64 v128, v77, 0, s[30:31]
	v_cndmask_b32_e64 v129, v78, 0, s[34:35]
	v_cndmask_b32_e64 v82, v79, 0, s[36:37]
	v_cndmask_b32_e64 v95, v80, 0, s[38:39]
	v_cndmask_b32_e64 v166, v81, 0, s[40:41]
	v_cvt_pk_bf16_f32 v126, v73, v74
	s_waitcnt lgkmcnt(1)
	v_mfma_f32_32x32x16_bf16 v[66:81], v[66:69], v[170:173], 0
	v_cvt_pk_bf16_f32 v127, v127, v128
	v_cvt_pk_bf16_f32 v128, v129, v82
	v_cvt_pk_bf16_f32 v129, v95, v166
	s_waitcnt lgkmcnt(0)
	s_nop 0
	v_mfma_f32_32x32x16_bf16 v[66:81], v[126:129], v[174:177], v[66:81]
	ds_read2_b64 v[126:129], v187 offset1:2
	s_waitcnt lgkmcnt(0)
	v_mfma_f32_32x32x16_bf16 v[66:81], v[126:129], v[50:53], v[66:81]
	ds_read2_b64 v[50:53], v187 offset0:4 offset1:6
	s_waitcnt lgkmcnt(0)
	v_mfma_f32_32x32x16_bf16 v[66:81], v[50:53], v[54:57], v[66:81]
	ds_read2_b64 v[50:53], v187 offset0:8 offset1:10
	s_waitcnt lgkmcnt(0)
	v_mfma_f32_32x32x16_bf16 v[66:81], v[50:53], v[2:5], v[66:81]
	ds_read2_b64 v[2:5], v187 offset0:12 offset1:14
	s_waitcnt lgkmcnt(0)
	v_mfma_f32_32x32x16_bf16 v[66:81], v[2:5], v[6:9], v[66:81]
	ds_read2_b64 v[2:5], v187 offset0:16 offset1:18
	v_cvt_pk_bf16_f32 v6, v18, v19
	v_cvt_pk_bf16_f32 v7, v20, v21
	v_cvt_pk_bf16_f32 v8, v22, v23
	v_cvt_pk_bf16_f32 v9, v24, v25
	s_waitcnt lgkmcnt(0)
	s_nop 0
	v_mfma_f32_32x32x16_bf16 v[66:81], v[2:5], v[6:9], v[66:81]
	ds_read2_b64 v[2:5], v187 offset0:20 offset1:22
	v_cvt_pk_bf16_f32 v6, v26, v27
	v_cvt_pk_bf16_f32 v7, v28, v29
	v_cvt_pk_bf16_f32 v8, v30, v31
	v_cvt_pk_bf16_f32 v9, v32, v33
	s_waitcnt lgkmcnt(0)
	s_nop 0
	v_mfma_f32_32x32x16_bf16 v[66:81], v[2:5], v[6:9], v[66:81]
	ds_read2_b64 v[2:5], v187 offset0:24 offset1:26
	v_cvt_pk_bf16_f32 v6, v34, v35
	v_cvt_pk_bf16_f32 v7, v36, v37
	v_cvt_pk_bf16_f32 v8, v38, v39
	v_cvt_pk_bf16_f32 v9, v40, v41
	s_waitcnt lgkmcnt(0)
	s_nop 0
	v_mfma_f32_32x32x16_bf16 v[66:81], v[2:5], v[6:9], v[66:81]
	ds_read2_b64 v[2:5], v187 offset0:28 offset1:30
	v_cvt_pk_bf16_f32 v6, v42, v43
	v_cvt_pk_bf16_f32 v7, v44, v45
	v_cvt_pk_bf16_f32 v8, v46, v47
	v_cvt_pk_bf16_f32 v9, v48, v49
	s_waitcnt lgkmcnt(0)
	s_nop 0
	v_mfma_f32_32x32x16_bf16 v[66:81], v[2:5], v[6:9], v[66:81]
	ds_read_u16 v2, v159
	v_add_u32_e32 v3, v159, v137
	v_add_u32_e32 v4, v159, v139
	s_waitcnt lgkmcnt(0)
	v_lshlrev_b32_e32 v2, 16, v2
	s_nop 6
	v_add_f32_e32 v2, v66, v2
	v_cvt_pk_bf16_f32 v2, v2, s0
	ds_write_b16 v159, v2
	ds_read_u16 v2, v3
	s_waitcnt lgkmcnt(0)
	v_lshlrev_b32_e32 v2, 16, v2
	v_add_f32_e32 v2, v67, v2
	v_cvt_pk_bf16_f32 v2, v2, s0
	ds_write_b16 v3, v2
	ds_read_u16 v2, v4
	v_add_u32_e32 v3, v159, v140
	s_waitcnt lgkmcnt(0)
	v_lshlrev_b32_e32 v2, 16, v2
	v_add_f32_e32 v2, v68, v2
	v_cvt_pk_bf16_f32 v2, v2, s0
	ds_write_b16 v4, v2
	ds_read_u16 v2, v3
	v_add_u32_e32 v4, v159, v141
	s_waitcnt lgkmcnt(0)
	v_lshlrev_b32_e32 v2, 16, v2
	v_add_f32_e32 v2, v69, v2
	v_cvt_pk_bf16_f32 v2, v2, s0
	ds_write_b16 v3, v2
	ds_read_u16 v2, v4
	v_add_u32_e32 v3, v159, v142
	s_waitcnt lgkmcnt(0)
	v_lshlrev_b32_e32 v2, 16, v2
	v_add_f32_e32 v2, v70, v2
	v_cvt_pk_bf16_f32 v2, v2, s0
	ds_write_b16 v4, v2
	ds_read_u16 v2, v3
	v_add_u32_e32 v4, v159, v143
	s_waitcnt lgkmcnt(0)
	v_lshlrev_b32_e32 v2, 16, v2
	v_add_f32_e32 v2, v71, v2
	v_cvt_pk_bf16_f32 v2, v2, s0
	ds_write_b16 v3, v2
	ds_read_u16 v2, v4
	v_add_u32_e32 v3, v159, v144
	s_waitcnt lgkmcnt(0)
	v_lshlrev_b32_e32 v2, 16, v2
	v_add_f32_e32 v2, v72, v2
	v_cvt_pk_bf16_f32 v2, v2, s0
	ds_write_b16 v4, v2
	ds_read_u16 v2, v3
	v_add_u32_e32 v4, v159, v145
	s_waitcnt lgkmcnt(0)
	v_lshlrev_b32_e32 v2, 16, v2
	v_add_f32_e32 v2, v73, v2
	v_cvt_pk_bf16_f32 v2, v2, s0
	ds_write_b16 v3, v2
	ds_read_u16 v2, v4
	v_add_u32_e32 v3, v159, v146
	s_waitcnt lgkmcnt(0)
	v_lshlrev_b32_e32 v2, 16, v2
	v_add_f32_e32 v2, v74, v2
	v_cvt_pk_bf16_f32 v2, v2, s0
	ds_write_b16 v4, v2
	ds_read_u16 v2, v3
	v_add_u32_e32 v4, v159, v147
	s_waitcnt lgkmcnt(0)
	v_lshlrev_b32_e32 v2, 16, v2
	v_add_f32_e32 v2, v75, v2
	v_cvt_pk_bf16_f32 v2, v2, s0
	ds_write_b16 v3, v2
	ds_read_u16 v2, v4
	v_add_u32_e32 v3, v159, v148
	s_waitcnt lgkmcnt(0)
	v_lshlrev_b32_e32 v2, 16, v2
	v_add_f32_e32 v2, v76, v2
	v_cvt_pk_bf16_f32 v2, v2, s0
	ds_write_b16 v4, v2
	ds_read_u16 v2, v3
	v_add_u32_e32 v4, v159, v149
	s_waitcnt lgkmcnt(0)
	v_lshlrev_b32_e32 v2, 16, v2
	v_add_f32_e32 v2, v77, v2
	v_cvt_pk_bf16_f32 v2, v2, s0
	ds_write_b16 v3, v2
	ds_read_u16 v2, v4
	v_add_u32_e32 v3, v159, v150
	s_waitcnt lgkmcnt(0)
	v_lshlrev_b32_e32 v2, 16, v2
	v_add_f32_e32 v2, v78, v2
	v_cvt_pk_bf16_f32 v2, v2, s0
	ds_write_b16 v4, v2
	ds_read_u16 v2, v3
	v_add_u32_e32 v4, v159, v151
	s_waitcnt lgkmcnt(0)
	v_lshlrev_b32_e32 v2, 16, v2
	v_add_f32_e32 v2, v79, v2
	v_cvt_pk_bf16_f32 v2, v2, s0
	ds_write_b16 v3, v2
	ds_read_u16 v2, v4
	s_waitcnt lgkmcnt(0)
	v_lshlrev_b32_e32 v2, 16, v2
	v_add_f32_e32 v2, v80, v2
	v_cvt_pk_bf16_f32 v2, v2, s0
	ds_write_b16 v4, v2
	v_add_u32_e32 v2, v159, v152
	ds_read_u16 v3, v2
	s_waitcnt lgkmcnt(0)
	v_lshlrev_b32_e32 v3, 16, v3
	v_add_f32_e32 v3, v81, v3
	v_cvt_pk_bf16_f32 v3, v3, s0
	ds_write_b16 v2, v3
	v_or_b32_e32 v22, s56, v153
	s_lshl_b32 s52, s46, 1
	v_ashrrev_i32_e32 v23, 31, v22
	v_lshl_add_u64 v[20:21], v[92:93], 0, s[52:53]
	v_lshlrev_b64 v[2:3], 11, v[22:23]
	v_lshl_add_u64 v[24:25], v[20:21], 0, v[2:3]
	s_waitcnt lgkmcnt(0)
	s_barrier
	s_barrier
	global_load_dwordx4 v[32:35], v[24:25], off
	v_add_co_u32_e32 v28, vcc, s91, v24
	v_or_b32_e32 v18, 64, v22
	s_nop 0
	v_addc_co_u32_e32 v29, vcc, 0, v25, vcc
	global_load_dwordx4 v[36:39], v[28:29], off
	global_load_dwordx4 v[2:5], v[90:91], off offset:16
	global_load_dwordx4 v[6:9], v[90:91], off
	ds_read_b128 v[40:43], v162
	ds_read_b128 v[44:47], v162 offset:8704
	ds_read_b128 v[14:17], v162 offset:17408
	ds_read_b128 v[10:13], v162 offset:26112
	v_ashrrev_i32_e32 v19, 31, v18
	s_waitcnt lgkmcnt(3)
	v_and_b32_e32 v55, 0xffff0000, v40
	s_waitcnt lgkmcnt(2)
	v_and_b32_e32 v63, 0xffff0000, v44
	v_lshlrev_b64 v[18:19], 11, v[18:19]
	v_lshlrev_b32_e32 v48, 16, v43
	v_and_b32_e32 v49, 0xffff0000, v43
	v_lshlrev_b32_e32 v50, 16, v42
	v_and_b32_e32 v51, 0xffff0000, v42
	v_lshlrev_b32_e32 v52, 16, v41
	v_and_b32_e32 v53, 0xffff0000, v41
	v_lshlrev_b32_e32 v54, 16, v40
	v_lshlrev_b32_e32 v56, 16, v47
	v_and_b32_e32 v57, 0xffff0000, v47
	v_lshlrev_b32_e32 v58, 16, v46
	v_and_b32_e32 v59, 0xffff0000, v46
	v_lshlrev_b32_e32 v60, 16, v45
	v_and_b32_e32 v61, 0xffff0000, v45
	v_lshlrev_b32_e32 v62, 16, v44
	v_mov_b32_e32 v66, v63
	v_mov_b32_e32 v67, v55
	v_lshl_add_u64 v[26:27], v[20:21], 0, v[18:19]
	v_pk_mul_f32 v[18:19], v[48:49], v[48:49]
	v_pk_mul_f32 v[30:31], v[50:51], v[50:51]
	v_pk_mul_f32 v[40:41], v[52:53], v[52:53]
	v_pk_mul_f32 v[42:43], v[56:57], v[56:57]
	v_pk_mul_f32 v[44:45], v[58:59], v[58:59]
	v_pk_mul_f32 v[46:47], v[60:61], v[60:61]
	v_mov_b32_e32 v64, v62
	v_mov_b32_e32 v65, v54
	v_pk_mul_f32 v[66:67], v[66:67], v[66:67]
	v_mov_b32_e32 v68, v46
	v_mov_b32_e32 v69, v40
	v_mov_b32_e32 v40, v47
	v_mov_b32_e32 v46, v44
	v_mov_b32_e32 v47, v30
	v_mov_b32_e32 v30, v45
	v_mov_b32_e32 v44, v42
	v_mov_b32_e32 v45, v18
	v_mov_b32_e32 v18, v43
	v_pk_fma_f32 v[42:43], v[64:65], v[64:65], v[66:67]
	s_add_i32 s95, s95, s70
	v_pk_add_f32 v[42:43], v[68:69], v[42:43]
	s_cmpk_lt_i32 s95, 0x100
	v_pk_add_f32 v[40:41], v[40:41], v[42:43]
	s_waitcnt vmcnt(3)
	v_lshlrev_b32_e32 v66, 16, v35
	v_pk_add_f32 v[40:41], v[46:47], v[40:41]
	v_and_b32_e32 v67, 0xffff0000, v35
	v_pk_add_f32 v[30:31], v[30:31], v[40:41]
	v_lshlrev_b32_e32 v68, 16, v34
	v_pk_add_f32 v[30:31], v[44:45], v[30:31]
	v_and_b32_e32 v69, 0xffff0000, v34
	v_pk_add_f32 v[18:19], v[18:19], v[30:31]
	ds_bpermute_b32 v65, v155, v19
	ds_bpermute_b32 v64, v155, v18
	v_add_co_u32_e32 v30, vcc, s92, v24
	v_lshlrev_b32_e32 v34, 16, v33
	s_nop 0
	v_addc_co_u32_e32 v31, vcc, 0, v25, vcc
	global_load_dwordx4 v[40:43], v[26:27], off
	global_load_dwordx4 v[44:47], v[30:31], off
	s_waitcnt lgkmcnt(0)
	v_pk_add_f32 v[18:19], v[18:19], v[64:65]
	ds_bpermute_b32 v65, v156, v19
	ds_bpermute_b32 v64, v156, v18
	v_and_b32_e32 v35, 0xffff0000, v33
	v_lshlrev_b32_e32 v70, 16, v32
	v_and_b32_e32 v71, 0xffff0000, v32
	s_waitcnt vmcnt(4)
	v_lshlrev_b32_e32 v72, 16, v39
	s_waitcnt lgkmcnt(0)
	v_pk_add_f32 v[18:19], v[18:19], v[64:65]
	ds_bpermute_b32 v65, v157, v19
	ds_bpermute_b32 v64, v157, v18
	v_and_b32_e32 v73, 0xffff0000, v39
	v_and_b32_e32 v39, 0xffff0000, v37
	v_lshlrev_b32_e32 v76, 16, v36
	v_and_b32_e32 v77, 0xffff0000, v36
	s_waitcnt lgkmcnt(0)
	v_pk_add_f32 v[18:19], v[18:19], v[64:65]
	ds_bpermute_b32 v33, v158, v19
	ds_bpermute_b32 v32, v158, v18
	v_lshlrev_b32_e32 v64, 16, v38
	v_and_b32_e32 v65, 0xffff0000, v38
	v_lshlrev_b32_e32 v38, 16, v37
	s_waitcnt lgkmcnt(0)
	v_pk_add_f32 v[32:33], v[18:19], v[32:33]
	v_mov_b64_e32 v[18:19], s[54:55]
	v_pk_fma_f32 v[74:75], v[32:33], s[50:51], v[18:19] op_sel_hi:[1,0,0]
	s_nop 0
	v_mul_f32_e32 v23, 0x4b800000, v75
	v_cmp_gt_f32_e32 vcc, s93, v75
	s_nop 1
	v_cndmask_b32_e32 v23, v75, v23, vcc
	v_rsq_f32_e32 v23, v23
	s_nop 0
	v_mul_f32_e32 v32, 0x45800000, v23
	v_cndmask_b32_e32 v32, v23, v32, vcc
	v_mul_f32_e32 v23, 0x4b800000, v74
	v_cmp_gt_f32_e32 vcc, s93, v74
	v_pk_mul_f32 v[36:37], v[32:33], v[54:55] op_sel_hi:[0,1]
	v_pk_mul_f32 v[52:53], v[32:33], v[52:53] op_sel_hi:[0,1]
	v_cndmask_b32_e32 v23, v74, v23, vcc
	v_pk_mul_f32 v[50:51], v[32:33], v[50:51] op_sel_hi:[0,1]
	v_pk_mul_f32 v[32:33], v[32:33], v[48:49] op_sel_hi:[0,1]
	v_rsq_f32_e32 v23, v23
	s_waitcnt vmcnt(2)
	v_pk_mul_f32 v[36:37], v[6:7], v[36:37]
	v_pk_mul_f32 v[52:53], v[8:9], v[52:53]
	v_pk_mul_f32 v[50:51], v[2:3], v[50:51]
	v_pk_mul_f32 v[32:33], v[4:5], v[32:33]
	v_pk_mul_f32 v[36:37], v[36:37], v[70:71]
	v_pk_mul_f32 v[34:35], v[52:53], v[34:35]
	v_pk_mul_f32 v[50:51], v[50:51], v[68:69]
	v_pk_mul_f32 v[48:49], v[32:33], v[66:67]
	v_cvt_pk_bf16_f32 v32, v36, v37
	v_cvt_pk_bf16_f32 v33, v34, v35
	v_cvt_pk_bf16_f32 v34, v50, v51
	v_cvt_pk_bf16_f32 v35, v48, v49
	global_store_dwordx4 v[24:25], v[32:35], off
	v_and_b32_e32 v67, 0xffff0000, v10
	v_lshlrev_b32_e32 v52, 16, v15
	v_mul_f32_e32 v32, 0x45800000, v23
	v_cndmask_b32_e32 v32, v23, v32, vcc
	v_pk_mul_f32 v[36:37], v[32:33], v[60:61] op_sel_hi:[0,1]
	v_pk_mul_f32 v[36:37], v[8:9], v[36:37]
	v_pk_mul_f32 v[34:35], v[32:33], v[62:63] op_sel_hi:[0,1]
	v_pk_mul_f32 v[36:37], v[36:37], v[38:39]
	v_pk_mul_f32 v[38:39], v[32:33], v[58:59] op_sel_hi:[0,1]
	v_pk_mul_f32 v[32:33], v[32:33], v[56:57] op_sel_hi:[0,1]
	v_and_b32_e32 v57, 0xffff0000, v14
	v_pk_mul_f32 v[38:39], v[2:3], v[38:39]
	v_and_b32_e32 v53, 0xffff0000, v15
	v_lshlrev_b32_e32 v56, 16, v14
	v_lshlrev_b32_e32 v62, 16, v11
	v_and_b32_e32 v63, 0xffff0000, v11
	v_lshlrev_b32_e32 v66, 16, v10
	v_mov_b32_e32 v68, v67
	v_mov_b32_e32 v69, v57
	v_pk_mul_f32 v[38:39], v[38:39], v[64:65]
	v_pk_mul_f32 v[54:55], v[52:53], v[52:53]
	v_pk_mul_f32 v[64:65], v[62:63], v[62:63]
	v_mov_b32_e32 v10, v66
	v_mov_b32_e32 v11, v56
	v_pk_mul_f32 v[68:69], v[68:69], v[68:69]
	v_pk_mul_f32 v[32:33], v[4:5], v[32:33]
	v_lshlrev_b32_e32 v50, 16, v16
	v_and_b32_e32 v51, 0xffff0000, v16
	v_lshlrev_b32_e32 v60, 16, v12
	v_and_b32_e32 v61, 0xffff0000, v12
	v_pk_fma_f32 v[10:11], v[10:11], v[10:11], v[68:69]
	v_mov_b32_e32 v68, v64
	v_mov_b32_e32 v69, v54
	v_pk_mul_f32 v[34:35], v[6:7], v[34:35]
	v_pk_mul_f32 v[48:49], v[32:33], v[72:73]
	v_cvt_pk_bf16_f32 v33, v36, v37
	v_lshlrev_b32_e32 v36, 16, v17
	v_and_b32_e32 v37, 0xffff0000, v17
	v_pk_mul_f32 v[16:17], v[50:51], v[50:51]
	v_lshlrev_b32_e32 v14, 16, v13
	v_and_b32_e32 v15, 0xffff0000, v13
	v_pk_mul_f32 v[12:13], v[60:61], v[60:61]
	v_pk_add_f32 v[10:11], v[68:69], v[10:11]
	v_mov_b32_e32 v54, v65
	v_pk_mul_f32 v[34:35], v[34:35], v[76:77]
	v_pk_add_f32 v[10:11], v[54:55], v[10:11]
	v_mov_b32_e32 v54, v12
	v_mov_b32_e32 v55, v16
	v_cvt_pk_bf16_f32 v32, v34, v35
	v_pk_mul_f32 v[34:35], v[36:37], v[36:37]
	v_pk_mul_f32 v[58:59], v[14:15], v[14:15]
	v_pk_add_f32 v[10:11], v[54:55], v[10:11]
	v_mov_b32_e32 v16, v13
	v_pk_add_f32 v[10:11], v[16:17], v[10:11]
	v_mov_b32_e32 v12, v58
	v_mov_b32_e32 v13, v34
	v_pk_add_f32 v[10:11], v[12:13], v[10:11]
	v_mov_b32_e32 v34, v59
	v_pk_add_f32 v[10:11], v[34:35], v[10:11]
	ds_bpermute_b32 v13, v155, v11
	ds_bpermute_b32 v12, v155, v10
	v_cvt_pk_bf16_f32 v34, v38, v39
	v_cvt_pk_bf16_f32 v35, v48, v49
	global_store_dwordx4 v[28:29], v[32:35], off
	s_waitcnt vmcnt(3)
	v_lshlrev_b32_e32 v16, 16, v43
	s_waitcnt lgkmcnt(0)
	v_pk_add_f32 v[10:11], v[10:11], v[12:13]
	ds_bpermute_b32 v13, v156, v11
	ds_bpermute_b32 v12, v156, v10
	v_and_b32_e32 v17, 0xffff0000, v43
	v_lshlrev_b32_e32 v28, 16, v42
	v_and_b32_e32 v29, 0xffff0000, v42
	v_lshlrev_b32_e32 v32, 16, v41
	s_waitcnt lgkmcnt(0)
	v_pk_add_f32 v[10:11], v[10:11], v[12:13]
	ds_bpermute_b32 v13, v157, v11
	ds_bpermute_b32 v12, v157, v10
	v_and_b32_e32 v33, 0xffff0000, v41
	v_lshlrev_b32_e32 v34, 16, v40
	v_and_b32_e32 v35, 0xffff0000, v40
	s_waitcnt vmcnt(2)
	v_lshlrev_b32_e32 v38, 16, v47
	s_waitcnt lgkmcnt(0)
	v_pk_add_f32 v[10:11], v[10:11], v[12:13]
	ds_bpermute_b32 v13, v158, v11
	ds_bpermute_b32 v12, v158, v10
	v_and_b32_e32 v39, 0xffff0000, v47
	v_lshlrev_b32_e32 v40, 16, v46
	v_and_b32_e32 v41, 0xffff0000, v46
	v_lshlrev_b32_e32 v42, 16, v45
	s_waitcnt lgkmcnt(0)
	v_pk_add_f32 v[10:11], v[10:11], v[12:13]
	v_and_b32_e32 v43, 0xffff0000, v45
	v_pk_fma_f32 v[12:13], v[10:11], s[50:51], v[18:19] op_sel_hi:[1,0,0]
	v_lshlrev_b32_e32 v46, 16, v44
	v_mul_f32_e32 v10, 0x4b800000, v13
	v_cmp_gt_f32_e32 vcc, s93, v13
	v_and_b32_e32 v47, 0xffff0000, v44
	s_nop 0
	v_cndmask_b32_e32 v10, v13, v10, vcc
	v_rsq_f32_e32 v10, v10
	v_mul_f32_e32 v13, 0x4b800000, v12
	v_mul_f32_e32 v11, 0x45800000, v10
	v_cndmask_b32_e32 v10, v10, v11, vcc
	v_pk_mul_f32 v[44:45], v[10:11], v[56:57] op_sel_hi:[0,1]
	v_pk_mul_f32 v[44:45], v[6:7], v[44:45]
	v_cmp_gt_f32_e32 vcc, s93, v12
	v_pk_mul_f32 v[34:35], v[44:45], v[34:35]
	v_pk_mul_f32 v[44:45], v[10:11], v[52:53] op_sel_hi:[0,1]
	v_pk_mul_f32 v[44:45], v[8:9], v[44:45]
	v_cndmask_b32_e32 v12, v12, v13, vcc
	v_pk_mul_f32 v[32:33], v[44:45], v[32:33]
	v_pk_mul_f32 v[44:45], v[10:11], v[50:51] op_sel_hi:[0,1]
	v_pk_mul_f32 v[10:11], v[10:11], v[36:37] op_sel_hi:[0,1]
	v_pk_mul_f32 v[10:11], v[4:5], v[10:11]
	v_pk_mul_f32 v[44:45], v[2:3], v[44:45]
	v_pk_mul_f32 v[16:17], v[10:11], v[16:17]
	v_pk_mul_f32 v[28:29], v[44:45], v[28:29]
	v_cvt_pk_bf16_f32 v13, v16, v17
	v_or_b32_e32 v16, 0x80, v22
	v_ashrrev_i32_e32 v17, 31, v16
	v_lshlrev_b64 v[16:17], 11, v[16:17]
	v_cvt_pk_bf16_f32 v10, v34, v35
	v_cvt_pk_bf16_f32 v11, v32, v33
	v_rsq_f32_e32 v23, v12
	v_cvt_pk_bf16_f32 v12, v28, v29
	v_lshl_add_u64 v[44:45], v[20:21], 0, v[16:17]
	global_store_dwordx4 v[26:27], v[10:13], off
	global_load_dwordx4 v[26:29], v[44:45], off
	s_nop 0
	v_mul_f32_e32 v10, 0x45800000, v23
	v_cndmask_b32_e32 v10, v23, v10, vcc
	v_pk_mul_f32 v[16:17], v[10:11], v[62:63] op_sel_hi:[0,1]
	v_pk_mul_f32 v[16:17], v[8:9], v[16:17]
	v_pk_mul_f32 v[12:13], v[10:11], v[66:67] op_sel_hi:[0,1]
	v_pk_mul_f32 v[36:37], v[16:17], v[42:43]
	v_pk_mul_f32 v[16:17], v[10:11], v[60:61] op_sel_hi:[0,1]
	v_pk_mul_f32 v[16:17], v[2:3], v[16:17]
	v_pk_mul_f32 v[10:11], v[10:11], v[14:15] op_sel_hi:[0,1]
	v_pk_mul_f32 v[40:41], v[16:17], v[40:41]
	v_add_co_u32_e32 v16, vcc, s94, v24
	v_pk_mul_f32 v[12:13], v[6:7], v[12:13]
	s_nop 0
	v_addc_co_u32_e32 v17, vcc, 0, v25, vcc
	global_load_dwordx4 v[32:35], v[16:17], off
	v_pk_mul_f32 v[10:11], v[4:5], v[10:11]
	v_pk_mul_f32 v[12:13], v[12:13], v[46:47]
	v_pk_mul_f32 v[14:15], v[10:11], v[38:39]
	v_cvt_pk_bf16_f32 v10, v12, v13
	v_cvt_pk_bf16_f32 v11, v36, v37
	v_cvt_pk_bf16_f32 v12, v40, v41
	v_cvt_pk_bf16_f32 v13, v14, v15
	global_store_dwordx4 v[30:31], v[10:13], off
	ds_read_b128 v[36:39], v162 offset:34816
	ds_read_b128 v[40:43], v162 offset:43520
	v_or_b32_e32 v10, 0xc0, v22
	v_ashrrev_i32_e32 v11, 31, v10
	v_add_u32_e32 v30, 0xe0, v22
	s_waitcnt lgkmcnt(1)
	v_and_b32_e32 v57, 0xffff0000, v36
	s_waitcnt lgkmcnt(0)
	v_and_b32_e32 v67, 0xffff0000, v40
	v_lshlrev_b32_e32 v52, 16, v37
	v_and_b32_e32 v53, 0xffff0000, v37
	v_lshlrev_b32_e32 v56, 16, v36
	v_lshlrev_b32_e32 v62, 16, v41
	v_and_b32_e32 v63, 0xffff0000, v41
	v_lshlrev_b32_e32 v66, 16, v40
	v_mov_b32_e32 v68, v67
	v_mov_b32_e32 v69, v57
	v_pk_mul_f32 v[54:55], v[52:53], v[52:53]
	v_pk_mul_f32 v[64:65], v[62:63], v[62:63]
	v_mov_b32_e32 v40, v66
	v_mov_b32_e32 v41, v56
	v_pk_mul_f32 v[68:69], v[68:69], v[68:69]
	v_lshlrev_b32_e32 v50, 16, v38
	v_and_b32_e32 v51, 0xffff0000, v38
	v_lshlrev_b32_e32 v60, 16, v42
	v_and_b32_e32 v61, 0xffff0000, v42
	v_pk_fma_f32 v[40:41], v[40:41], v[40:41], v[68:69]
	v_mov_b32_e32 v68, v64
	v_mov_b32_e32 v69, v54
	v_lshlrev_b32_e32 v46, 16, v39
	v_and_b32_e32 v47, 0xffff0000, v39
	v_pk_mul_f32 v[38:39], v[50:51], v[50:51]
	v_lshlrev_b32_e32 v58, 16, v43
	v_and_b32_e32 v59, 0xffff0000, v43
	v_pk_mul_f32 v[42:43], v[60:61], v[60:61]
	v_pk_add_f32 v[40:41], v[68:69], v[40:41]
	v_mov_b32_e32 v54, v65
	v_pk_add_f32 v[40:41], v[54:55], v[40:41]
	v_mov_b32_e32 v54, v42
	v_mov_b32_e32 v55, v38
	v_pk_mul_f32 v[48:49], v[46:47], v[46:47]
	v_pk_mul_f32 v[36:37], v[58:59], v[58:59]
	v_pk_add_f32 v[40:41], v[54:55], v[40:41]
	v_mov_b32_e32 v38, v43
	v_pk_add_f32 v[38:39], v[38:39], v[40:41]
	v_mov_b32_e32 v40, v36
	v_mov_b32_e32 v41, v48
	v_pk_add_f32 v[38:39], v[40:41], v[38:39]
	v_mov_b32_e32 v48, v37
	v_pk_add_f32 v[48:49], v[48:49], v[38:39]
	ds_bpermute_b32 v55, v155, v49
	ds_bpermute_b32 v54, v155, v48
	v_lshlrev_b64 v[10:11], 11, v[10:11]
	v_ashrrev_i32_e32 v31, 31, v30
	v_lshl_add_u64 v[14:15], v[20:21], 0, v[10:11]
	v_lshlrev_b64 v[30:31], 11, v[30:31]
	s_waitcnt lgkmcnt(0)
	v_pk_add_f32 v[48:49], v[48:49], v[54:55]
	ds_bpermute_b32 v55, v156, v49
	ds_bpermute_b32 v54, v156, v48
	ds_read_b128 v[22:25], v162 offset:52224
	ds_read_b128 v[10:13], v162 offset:60928
	v_lshl_add_u64 v[20:21], v[20:21], 0, v[30:31]
	global_load_dwordx4 v[36:39], v[14:15], off
	global_load_dwordx4 v[40:43], v[20:21], off
	s_waitcnt vmcnt(4)
	v_lshlrev_b32_e32 v30, 16, v29
	s_waitcnt lgkmcnt(2)
	v_pk_add_f32 v[48:49], v[48:49], v[54:55]
	ds_bpermute_b32 v55, v157, v49
	ds_bpermute_b32 v54, v157, v48
	v_and_b32_e32 v31, 0xffff0000, v29
	v_lshlrev_b32_e32 v64, 16, v28
	v_and_b32_e32 v65, 0xffff0000, v28
	v_lshlrev_b32_e32 v28, 16, v27
	v_and_b32_e32 v29, 0xffff0000, v27
	v_lshlrev_b32_e32 v68, 16, v26
	v_and_b32_e32 v69, 0xffff0000, v26
	s_waitcnt lgkmcnt(0)
	v_pk_add_f32 v[26:27], v[48:49], v[54:55]
	ds_bpermute_b32 v49, v158, v27
	ds_bpermute_b32 v48, v158, v26
	s_waitcnt vmcnt(3)
	v_lshlrev_b32_e32 v70, 16, v35
	v_and_b32_e32 v71, 0xffff0000, v35
	v_lshlrev_b32_e32 v54, 16, v34
	v_and_b32_e32 v55, 0xffff0000, v34
	s_waitcnt lgkmcnt(0)
	v_pk_add_f32 v[26:27], v[26:27], v[48:49]
	v_lshlrev_b32_e32 v34, 16, v33
	v_pk_fma_f32 v[48:49], v[26:27], s[50:51], v[18:19] op_sel_hi:[1,0,0]
	v_and_b32_e32 v35, 0xffff0000, v33
	v_mul_f32_e32 v26, 0x4b800000, v49
	v_cmp_gt_f32_e32 vcc, s93, v49
	v_lshlrev_b32_e32 v72, 16, v32
	v_and_b32_e32 v73, 0xffff0000, v32
	v_cndmask_b32_e32 v26, v49, v26, vcc
	v_rsq_f32_e32 v26, v26
	s_nop 0
	v_mul_f32_e32 v27, 0x45800000, v26
	v_cndmask_b32_e32 v26, v26, v27, vcc
	v_pk_mul_f32 v[52:53], v[26:27], v[52:53] op_sel_hi:[0,1]
	v_pk_mul_f32 v[32:33], v[26:27], v[56:57] op_sel_hi:[0,1]
	v_pk_mul_f32 v[52:53], v[8:9], v[52:53]
	v_pk_mul_f32 v[50:51], v[26:27], v[50:51] op_sel_hi:[0,1]
	v_pk_mul_f32 v[26:27], v[26:27], v[46:47] op_sel_hi:[0,1]
	v_pk_mul_f32 v[28:29], v[52:53], v[28:29]
	v_pk_mul_f32 v[26:27], v[4:5], v[26:27]
	v_pk_mul_f32 v[32:33], v[6:7], v[32:33]
	v_pk_mul_f32 v[30:31], v[26:27], v[30:31]
	v_cvt_pk_bf16_f32 v27, v28, v29
	v_mul_f32_e32 v28, 0x4b800000, v48
	v_cmp_gt_f32_e32 vcc, s93, v48
	v_pk_mul_f32 v[32:33], v[32:33], v[68:69]
	v_pk_mul_f32 v[50:51], v[2:3], v[50:51]
	v_cndmask_b32_e32 v28, v48, v28, vcc
	v_cvt_pk_bf16_f32 v26, v32, v33
	v_rsq_f32_e32 v32, v28
	v_pk_mul_f32 v[50:51], v[50:51], v[64:65]
	v_cvt_pk_bf16_f32 v29, v30, v31
	v_cvt_pk_bf16_f32 v28, v50, v51
	global_store_dwordx4 v[44:45], v[26:29], off
	v_and_b32_e32 v51, 0xffff0000, v22
	v_lshlrev_b32_e32 v46, 16, v23
	v_mul_f32_e32 v26, 0x45800000, v32
	v_cndmask_b32_e32 v26, v32, v26, vcc
	v_pk_mul_f32 v[32:33], v[26:27], v[60:61] op_sel_hi:[0,1]
	v_and_b32_e32 v61, 0xffff0000, v10
	v_pk_mul_f32 v[30:31], v[26:27], v[62:63] op_sel_hi:[0,1]
	v_and_b32_e32 v47, 0xffff0000, v23
	v_lshlrev_b32_e32 v50, 16, v22
	v_lshlrev_b32_e32 v56, 16, v11
	v_and_b32_e32 v57, 0xffff0000, v11
	v_lshlrev_b32_e32 v60, 16, v10
	v_mov_b32_e32 v62, v61
	v_mov_b32_e32 v63, v51
	v_pk_mul_f32 v[28:29], v[26:27], v[66:67] op_sel_hi:[0,1]
	v_pk_mul_f32 v[30:31], v[8:9], v[30:31]
	v_pk_mul_f32 v[32:33], v[2:3], v[32:33]
	v_pk_mul_f32 v[26:27], v[26:27], v[58:59] op_sel_hi:[0,1]
	v_pk_mul_f32 v[48:49], v[46:47], v[46:47]
	v_pk_mul_f32 v[58:59], v[56:57], v[56:57]
	v_mov_b32_e32 v10, v60
	v_mov_b32_e32 v11, v50
	v_pk_mul_f32 v[62:63], v[62:63], v[62:63]
	v_pk_mul_f32 v[30:31], v[30:31], v[34:35]
	v_pk_mul_f32 v[32:33], v[32:33], v[54:55]
	v_pk_mul_f32 v[26:27], v[4:5], v[26:27]
	v_lshlrev_b32_e32 v44, 16, v24
	v_and_b32_e32 v45, 0xffff0000, v24
	v_lshlrev_b32_e32 v54, 16, v12
	v_and_b32_e32 v55, 0xffff0000, v12
	v_pk_fma_f32 v[10:11], v[10:11], v[10:11], v[62:63]
	v_mov_b32_e32 v62, v58
	v_mov_b32_e32 v63, v48
	v_pk_mul_f32 v[28:29], v[6:7], v[28:29]
	v_pk_mul_f32 v[34:35], v[26:27], v[70:71]
	v_cvt_pk_bf16_f32 v27, v30, v31
	v_lshlrev_b32_e32 v30, 16, v25
	v_and_b32_e32 v31, 0xffff0000, v25
	v_pk_mul_f32 v[24:25], v[44:45], v[44:45]
	v_lshlrev_b32_e32 v22, 16, v13
	v_and_b32_e32 v23, 0xffff0000, v13
	v_pk_mul_f32 v[12:13], v[54:55], v[54:55]
	v_pk_add_f32 v[10:11], v[62:63], v[10:11]
	v_mov_b32_e32 v48, v59
	v_pk_mul_f32 v[28:29], v[28:29], v[72:73]
	v_pk_add_f32 v[10:11], v[48:49], v[10:11]
	v_mov_b32_e32 v48, v12
	v_mov_b32_e32 v49, v24
	v_cvt_pk_bf16_f32 v26, v28, v29
	v_pk_mul_f32 v[28:29], v[30:31], v[30:31]
	v_pk_mul_f32 v[52:53], v[22:23], v[22:23]
	v_pk_add_f32 v[10:11], v[48:49], v[10:11]
	v_mov_b32_e32 v24, v13
	v_pk_add_f32 v[10:11], v[24:25], v[10:11]
	v_mov_b32_e32 v12, v52
	v_mov_b32_e32 v13, v28
	v_pk_add_f32 v[10:11], v[12:13], v[10:11]
	v_mov_b32_e32 v28, v53
	v_pk_add_f32 v[10:11], v[28:29], v[10:11]
	ds_bpermute_b32 v13, v155, v11
	ds_bpermute_b32 v12, v155, v10
	v_cvt_pk_bf16_f32 v28, v32, v33
	v_cvt_pk_bf16_f32 v29, v34, v35
	global_store_dwordx4 v[16:17], v[26:29], off
	s_waitcnt vmcnt(3)
	v_lshlrev_b32_e32 v16, 16, v39
	s_waitcnt lgkmcnt(0)
	v_pk_add_f32 v[10:11], v[10:11], v[12:13]
	ds_bpermute_b32 v13, v156, v11
	ds_bpermute_b32 v12, v156, v10
	v_and_b32_e32 v17, 0xffff0000, v39
	v_lshlrev_b32_e32 v24, 16, v38
	v_and_b32_e32 v25, 0xffff0000, v38
	v_lshlrev_b32_e32 v28, 16, v36
	s_waitcnt lgkmcnt(0)
	v_pk_add_f32 v[10:11], v[10:11], v[12:13]
	ds_bpermute_b32 v13, v157, v11
	ds_bpermute_b32 v12, v157, v10
	v_and_b32_e32 v29, 0xffff0000, v36
	v_lshlrev_b32_e32 v26, 16, v37
	v_and_b32_e32 v27, 0xffff0000, v37
	s_waitcnt vmcnt(2)
	v_lshlrev_b32_e32 v34, 16, v42
	s_waitcnt lgkmcnt(0)
	v_pk_add_f32 v[10:11], v[10:11], v[12:13]
	ds_bpermute_b32 v13, v158, v11
	ds_bpermute_b32 v12, v158, v10
	v_and_b32_e32 v35, 0xffff0000, v42
	v_lshlrev_b32_e32 v32, 16, v43
	v_and_b32_e32 v33, 0xffff0000, v43
	v_lshlrev_b32_e32 v36, 16, v41
	s_waitcnt lgkmcnt(0)
	v_pk_add_f32 v[10:11], v[10:11], v[12:13]
	v_and_b32_e32 v37, 0xffff0000, v41
	v_pk_fma_f32 v[12:13], v[10:11], s[50:51], v[18:19] op_sel_hi:[1,0,0]
	v_lshlrev_b32_e32 v18, 16, v40
	v_mul_f32_e32 v10, 0x4b800000, v13
	v_cmp_gt_f32_e32 vcc, s93, v13
	v_and_b32_e32 v19, 0xffff0000, v40
	s_nop 0
	v_cndmask_b32_e32 v10, v13, v10, vcc
	v_rsq_f32_e32 v10, v10
	v_mul_f32_e32 v13, 0x4b800000, v12
	v_mul_f32_e32 v11, 0x45800000, v10
	v_cndmask_b32_e32 v10, v10, v11, vcc
	v_pk_mul_f32 v[38:39], v[10:11], v[50:51] op_sel_hi:[0,1]
	v_pk_mul_f32 v[38:39], v[6:7], v[38:39]
	v_cmp_gt_f32_e32 vcc, s93, v12
	v_pk_mul_f32 v[28:29], v[38:39], v[28:29]
	v_pk_mul_f32 v[38:39], v[10:11], v[46:47] op_sel_hi:[0,1]
	v_pk_mul_f32 v[38:39], v[8:9], v[38:39]
	v_cndmask_b32_e32 v12, v12, v13, vcc
	v_pk_mul_f32 v[26:27], v[38:39], v[26:27]
	v_pk_mul_f32 v[38:39], v[10:11], v[44:45] op_sel_hi:[0,1]
	v_pk_mul_f32 v[10:11], v[10:11], v[30:31] op_sel_hi:[0,1]
	v_pk_mul_f32 v[10:11], v[4:5], v[10:11]
	v_pk_mul_f32 v[38:39], v[2:3], v[38:39]
	v_pk_mul_f32 v[16:17], v[10:11], v[16:17]
	v_cvt_pk_bf16_f32 v11, v26, v27
	v_rsq_f32_e32 v26, v12
	v_pk_mul_f32 v[24:25], v[38:39], v[24:25]
	v_cvt_pk_bf16_f32 v10, v28, v29
	v_cvt_pk_bf16_f32 v12, v24, v25
	v_cvt_pk_bf16_f32 v13, v16, v17
	global_store_dwordx4 v[14:15], v[10:13], off
	s_nop 1
	v_mul_f32_e32 v10, 0x45800000, v26
	v_cndmask_b32_e32 v10, v26, v10, vcc
	v_pk_mul_f32 v[12:13], v[10:11], v[60:61] op_sel_hi:[0,1]
	v_pk_mul_f32 v[6:7], v[6:7], v[12:13]
	v_pk_mul_f32 v[12:13], v[10:11], v[56:57] op_sel_hi:[0,1]
	v_pk_mul_f32 v[8:9], v[8:9], v[12:13]
	v_pk_mul_f32 v[12:13], v[10:11], v[54:55] op_sel_hi:[0,1]
	v_pk_mul_f32 v[2:3], v[2:3], v[12:13]
	v_pk_mul_f32 v[6:7], v[6:7], v[18:19]
	v_pk_mul_f32 v[12:13], v[2:3], v[34:35]
	v_pk_mul_f32 v[2:3], v[10:11], v[22:23] op_sel_hi:[0,1]
	v_pk_mul_f32 v[2:3], v[4:5], v[2:3]
	v_pk_mul_f32 v[8:9], v[8:9], v[36:37]
	v_pk_mul_f32 v[10:11], v[2:3], v[32:33]
	v_cvt_pk_bf16_f32 v2, v6, v7
	v_cvt_pk_bf16_f32 v3, v8, v9
	v_cvt_pk_bf16_f32 v4, v12, v13
	v_cvt_pk_bf16_f32 v5, v10, v11
	global_store_dwordx4 v[20:21], v[2:5], off
	s_barrier
	s_cbranch_scc0 .LBB0_940
